# in-projection epilogue: units with output scale exactly 1.0 (K/V/Z tiles) take a copy of the epilogue without the 128 multiplies by 1.0
# baseline (speedup 1.0000x reference)
; __device__ __forceinline__ unsigned cvt_pk_bf16(float lo, float hi) { unsigned r; asm volatile("v_cvt_pk_bf16_f32 %0, %1, %2" : "=v"(r) : "v"(lo), "v"(hi)); return r; }
;     __device__ __forceinline__ void operator()(const pg8::f32x4 (&acc_)[2][2][4][2], const pg8::Unit& u, int, int wr, int wc, int fr, int fq) const {
;         const int kind = u.pn >> 2, cc0 = (u.pn & 3) * 256 + wc * 32 + 8 * fq;
;         const bool samp = (u.pm == MP / 256);
;         bf16* bbuf = kind == 0 ? qb : kind == 1 ? kb : kind == 2 ? vb : zb;
;         const float sc = kind == 0 ? C2 : 1.0f;
;         pg8::f32x4 acc[2][2][4][2];
; #pragma unroll
;         for (int ai = 0; ai < 2; ++ai)
; #pragma unroll
;             for (int m = 0; m < 4; ++m) { const float rs = rstd ? rstd[u.pm * 256 + ai * 128 + wr * 64 + m * 16 + fr] : 1.0f;
; #pragma unroll
;                 for (int bj = 0; bj < 2; ++bj)
; #pragma unroll
;                     for (int n = 0; n < 2; ++n) acc[ai][bj][m][n] = acc_[ai][bj][m][n] * rs; }
; #pragma unroll
;         for (int ai = 0; ai < 2; ++ai)
; #pragma unroll
;             for (int m = 0; m < 4; ++m) {
;                 const int grow = u.pm * 256 + ai * 128 + wr * 64 + m * 16 + fr;
; #pragma unroll
;                 for (int bj = 0; bj < 2; ++bj) {
;                     const int cc = cc0 + bj * 128;
;                     const pg8::f32x4 v0 = acc[ai][bj][m][0], v1 = acc[ai][bj][m][1];
;                     u32x4 w; w.x = pg8::cvt_pk_bf16(v0[0] * sc, v0[1] * sc); w.y = pg8::cvt_pk_bf16(v0[2] * sc, v0[3] * sc); w.z = pg8::cvt_pk_bf16(v1[0] * sc, v1[1] * sc); w.w = pg8::cvt_pk_bf16(v1[2] * sc, v1[3] * sc);
;                     *(u32x4*)(bbuf + (size_t)grow * D + cc) = w;
.LBB0_193:
	s_cmp_eq_u32 s21, 1.0
	s_cbranch_scc1 .Lepi1_l0
	s_lshl_b32 s23, s51, 8
	s_and_b32 s23, s23, 0x300
	v_or_b32_e32 v138, s23, v156
	s_lshl_b32 s23, s28, 8
	v_add_u32_e32 v160, s23, v1
	v_ashrrev_i32_e32 v161, 31, v160
	v_mul_f32_e32 v126, s21, v126
	v_mul_f32_e32 v127, s21, v127
	v_lshlrev_b64 v[160:161], 11, v[160:161]
	v_cvt_pk_bf16_f32 v126, v126, v127
	v_mul_f32_e32 v127, s21, v128
	v_mul_f32_e32 v128, s21, v129
	v_mul_f32_e32 v122, s21, v122
	v_mul_f32_e32 v123, s21, v123
	v_lshl_add_u64 v[160:161], s[2:3], 0, v[160:161]
	v_cvt_pk_bf16_f32 v127, v127, v128
	v_cvt_pk_bf16_f32 v128, v122, v123
	v_mul_f32_e32 v122, s21, v124
	v_mul_f32_e32 v123, s21, v125
	v_lshlrev_b32_e32 v138, 1, v138
	v_cvt_pk_bf16_f32 v129, v122, v123
	v_lshl_add_u64 v[122:123], v[160:161], 0, v[138:139]
	v_mul_f32_e32 v114, s21, v114
	v_mul_f32_e32 v115, s21, v115
	global_store_dwordx4 v[122:123], v[126:129], off
	v_cvt_pk_bf16_f32 v114, v114, v115
	v_mul_f32_e32 v115, s21, v116
	v_mul_f32_e32 v116, s21, v117
	v_mul_f32_e32 v106, s21, v106
	v_cvt_pk_bf16_f32 v115, v115, v116
	v_mul_f32_e32 v107, s21, v107
	v_cvt_pk_bf16_f32 v116, v106, v107
	v_mul_f32_e32 v106, s21, v108
	v_mul_f32_e32 v107, s21, v109
	v_cvt_pk_bf16_f32 v117, v106, v107
	v_add_u32_e32 v106, s23, v149
	v_ashrrev_i32_e32 v107, 31, v106
	v_lshlrev_b64 v[106:107], 11, v[106:107]
	global_store_dwordx4 v[122:123], v[114:117], off offset:256
	v_mul_f32_e32 v108, s21, v121
	v_mul_f32_e32 v109, s21, v111
	v_lshl_add_u64 v[114:115], s[2:3], 0, v[106:107]
	v_mul_f32_e32 v106, s21, v118
	v_mul_f32_e32 v107, s21, v119
	v_cvt_pk_bf16_f32 v106, v106, v107
	v_mul_f32_e32 v107, s21, v120
	v_cvt_pk_bf16_f32 v107, v107, v108
	v_mul_f32_e32 v108, s21, v110
	v_cvt_pk_bf16_f32 v108, v108, v109
	v_mul_f32_e32 v109, s21, v112
	v_mul_f32_e32 v110, s21, v113
	v_cvt_pk_bf16_f32 v109, v109, v110
	v_lshl_add_u64 v[110:111], v[114:115], 0, v[138:139]
	v_mul_f32_e32 v98, s21, v98
	v_mul_f32_e32 v99, s21, v99
	global_store_dwordx4 v[110:111], v[106:109], off
	v_cvt_pk_bf16_f32 v98, v98, v99
	v_mul_f32_e32 v99, s21, v100
	v_mul_f32_e32 v100, s21, v101
	v_mul_f32_e32 v90, s21, v90
	v_cvt_pk_bf16_f32 v99, v99, v100
	v_mul_f32_e32 v91, s21, v91
	v_cvt_pk_bf16_f32 v100, v90, v91
	v_mul_f32_e32 v90, s21, v92
	v_mul_f32_e32 v91, s21, v93
	v_cvt_pk_bf16_f32 v101, v90, v91
	v_add_u32_e32 v90, s23, v150
	v_ashrrev_i32_e32 v91, 31, v90
	v_lshlrev_b64 v[90:91], 11, v[90:91]
	global_store_dwordx4 v[110:111], v[98:101], off offset:256
	v_mul_f32_e32 v92, s21, v105
	v_mul_f32_e32 v93, s21, v95
	v_lshl_add_u64 v[98:99], s[2:3], 0, v[90:91]
	v_mul_f32_e32 v90, s21, v102
	v_mul_f32_e32 v91, s21, v103
	v_cvt_pk_bf16_f32 v90, v90, v91
	v_mul_f32_e32 v91, s21, v104
	v_cvt_pk_bf16_f32 v91, v91, v92
	v_mul_f32_e32 v92, s21, v94
	v_cvt_pk_bf16_f32 v92, v92, v93
	v_mul_f32_e32 v93, s21, v96
	v_mul_f32_e32 v94, s21, v97
	v_cvt_pk_bf16_f32 v93, v93, v94
	v_lshl_add_u64 v[94:95], v[98:99], 0, v[138:139]
	v_mul_f32_e32 v82, s21, v82
	v_mul_f32_e32 v83, s21, v83
	global_store_dwordx4 v[94:95], v[90:93], off
	v_cvt_pk_bf16_f32 v82, v82, v83
	v_mul_f32_e32 v83, s21, v84
	v_mul_f32_e32 v84, s21, v85
	v_mul_f32_e32 v74, s21, v74
	v_cvt_pk_bf16_f32 v83, v83, v84
	v_mul_f32_e32 v75, s21, v75
	v_cvt_pk_bf16_f32 v84, v74, v75
	v_mul_f32_e32 v74, s21, v76
	v_mul_f32_e32 v75, s21, v77
	v_cvt_pk_bf16_f32 v85, v74, v75
	v_add_u32_e32 v74, s23, v151
	v_ashrrev_i32_e32 v75, 31, v74
	v_lshlrev_b64 v[74:75], 11, v[74:75]
	global_store_dwordx4 v[94:95], v[82:85], off offset:256
	v_mul_f32_e32 v76, s21, v89
	v_mul_f32_e32 v77, s21, v79
	v_lshl_add_u64 v[82:83], s[2:3], 0, v[74:75]
	v_mul_f32_e32 v74, s21, v86
	v_mul_f32_e32 v75, s21, v87
	v_cvt_pk_bf16_f32 v74, v74, v75
	v_mul_f32_e32 v75, s21, v88
	v_cvt_pk_bf16_f32 v75, v75, v76
	v_mul_f32_e32 v76, s21, v78
	v_cvt_pk_bf16_f32 v76, v76, v77
	v_mul_f32_e32 v77, s21, v80
	v_mul_f32_e32 v78, s21, v81
	v_cvt_pk_bf16_f32 v77, v77, v78
	v_lshl_add_u64 v[78:79], v[82:83], 0, v[138:139]
	v_mul_f32_e32 v70, s21, v70
	v_mul_f32_e32 v71, s21, v71
	global_store_dwordx4 v[78:79], v[74:77], off
	v_cvt_pk_bf16_f32 v70, v70, v71
	v_mul_f32_e32 v71, s21, v72
	v_mul_f32_e32 v72, s21, v73
	v_mul_f32_e32 v66, s21, v66
	v_cvt_pk_bf16_f32 v71, v71, v72
	v_mul_f32_e32 v67, s21, v67
	v_cvt_pk_bf16_f32 v72, v66, v67
	v_mul_f32_e32 v66, s21, v68
	v_mul_f32_e32 v67, s21, v69
	v_cvt_pk_bf16_f32 v73, v66, v67
	v_add_u32_e32 v66, s23, v152
	v_ashrrev_i32_e32 v67, 31, v66
	v_mul_f32_e32 v62, s21, v62
	v_mul_f32_e32 v63, s21, v63
	global_store_dwordx4 v[78:79], v[70:73], off offset:256
	v_lshlrev_b64 v[66:67], 11, v[66:67]
	v_cvt_pk_bf16_f32 v62, v62, v63
	v_mul_f32_e32 v63, s21, v64
	v_mul_f32_e32 v64, s21, v65
	v_mul_f32_e32 v58, s21, v58
	v_mul_f32_e32 v59, s21, v59
	v_lshl_add_u64 v[66:67], s[2:3], 0, v[66:67]
	v_cvt_pk_bf16_f32 v63, v63, v64
	v_cvt_pk_bf16_f32 v64, v58, v59
	v_mul_f32_e32 v58, s21, v60
	v_mul_f32_e32 v59, s21, v61
	v_cvt_pk_bf16_f32 v65, v58, v59
	v_lshl_add_u64 v[58:59], v[66:67], 0, v[138:139]
	v_mul_f32_e32 v50, s21, v50
	v_mul_f32_e32 v51, s21, v51
	global_store_dwordx4 v[58:59], v[62:65], off
	v_cvt_pk_bf16_f32 v50, v50, v51
	v_mul_f32_e32 v51, s21, v52
	v_mul_f32_e32 v52, s21, v53
	v_mul_f32_e32 v42, s21, v42
	v_cvt_pk_bf16_f32 v51, v51, v52
	v_mul_f32_e32 v43, s21, v43
	v_cvt_pk_bf16_f32 v52, v42, v43
	v_mul_f32_e32 v42, s21, v44
	v_mul_f32_e32 v43, s21, v45
	v_cvt_pk_bf16_f32 v53, v42, v43
	v_add_u32_e32 v42, s23, v153
	v_ashrrev_i32_e32 v43, 31, v42
	v_lshlrev_b64 v[42:43], 11, v[42:43]
	global_store_dwordx4 v[58:59], v[50:53], off offset:256
	v_mul_f32_e32 v44, s21, v57
	v_mul_f32_e32 v45, s21, v47
; __device__ __forceinline__ unsigned cvt_pk_bf16(float lo, float hi) { unsigned r; asm volatile("v_cvt_pk_bf16_f32 %0, %1, %2" : "=v"(r) : "v"(lo), "v"(hi)); return r; }
; #define PG8_BAR __builtin_amdgcn_s_barrier()
; template <class Epi, class Sched, bool ALIGN_EPI = false, bool SP2 = false>
; __device__ __forceinline__ void gemm_phase(PG8_LAS unsigned char* lds, const Gemm g, const Sched& S, const Epi& E) {
;     ...
;         if constexpr (!Epi::AFTER_DRAIN) { E(acc, cur, ui, wr, wc, fr, fq); S.done(cur); }
;         if (!has_next) break;
; #pragma unroll
;         for (int a = 0; a < 2; ++a)
; #pragma unroll
;             for (int b = 0; b < 2; ++b)
; #pragma unroll
;                 for (int m = 0; m < 4; ++m)
; #pragma unroll
;                     for (int n = 0; n < 2; ++n) acc[a][b][m][n] = (f32x4){0.f, 0.f, 0.f, 0.f};
;         cur = nxt; cA = nA; cB = nB; ++ui;
;         if constexpr (ALIGN_EPI) { if (wr == 1) PG8_BAR; }
;     }
;     __device__ __forceinline__ void operator()(const pg8::f32x4 (&acc_)[2][2][4][2], const pg8::Unit& u, int, int wr, int wc, int fr, int fq) const {
;     ...
;         for (int ai = 0; ai < 2; ++ai)
; #pragma unroll
;             for (int m = 0; m < 4; ++m) {
;                 const int grow = u.pm * 256 + ai * 128 + wr * 64 + m * 16 + fr;
; #pragma unroll
;                 for (int bj = 0; bj < 2; ++bj) {
;                     const int cc = cc0 + bj * 128;
;                     const pg8::f32x4 v0 = acc[ai][bj][m][0], v1 = acc[ai][bj][m][1];
;                     u32x4 w; w.x = pg8::cvt_pk_bf16(v0[0] * sc, v0[1] * sc); w.y = pg8::cvt_pk_bf16(v0[2] * sc, v0[3] * sc); w.z = pg8::cvt_pk_bf16(v1[0] * sc, v1[1] * sc); w.w = pg8::cvt_pk_bf16(v1[2] * sc, v1[3] * sc);
;                     *(u32x4*)(bbuf + (size_t)grow * D + cc) = w;
	v_lshl_add_u64 v[50:51], s[2:3], 0, v[42:43]
	v_mul_f32_e32 v42, s21, v54
	v_mul_f32_e32 v43, s21, v55
	v_cvt_pk_bf16_f32 v42, v42, v43
	v_mul_f32_e32 v43, s21, v56
	v_cvt_pk_bf16_f32 v43, v43, v44
	v_mul_f32_e32 v44, s21, v46
	v_cvt_pk_bf16_f32 v44, v44, v45
	v_mul_f32_e32 v45, s21, v48
	v_mul_f32_e32 v46, s21, v49
	v_cvt_pk_bf16_f32 v45, v45, v46
	v_lshl_add_u64 v[46:47], v[50:51], 0, v[138:139]
	v_mul_f32_e32 v34, s21, v34
	v_mul_f32_e32 v35, s21, v35
	global_store_dwordx4 v[46:47], v[42:45], off
	v_cvt_pk_bf16_f32 v34, v34, v35
	v_mul_f32_e32 v35, s21, v36
	v_mul_f32_e32 v36, s21, v37
	v_mul_f32_e32 v26, s21, v26
	v_cvt_pk_bf16_f32 v35, v35, v36
	v_mul_f32_e32 v27, s21, v27
	v_cvt_pk_bf16_f32 v36, v26, v27
	v_mul_f32_e32 v26, s21, v28
	v_mul_f32_e32 v27, s21, v29
	v_cvt_pk_bf16_f32 v37, v26, v27
	v_add_u32_e32 v26, s23, v154
	v_ashrrev_i32_e32 v27, 31, v26
	v_lshlrev_b64 v[26:27], 11, v[26:27]
	global_store_dwordx4 v[46:47], v[34:37], off offset:256
	v_mul_f32_e32 v28, s21, v41
	v_mul_f32_e32 v29, s21, v31
	v_lshl_add_u64 v[34:35], s[2:3], 0, v[26:27]
	v_mul_f32_e32 v26, s21, v38
	v_mul_f32_e32 v27, s21, v39
	v_cvt_pk_bf16_f32 v26, v26, v27
	v_mul_f32_e32 v27, s21, v40
	v_cvt_pk_bf16_f32 v27, v27, v28
	v_mul_f32_e32 v28, s21, v30
	v_cvt_pk_bf16_f32 v28, v28, v29
	v_mul_f32_e32 v29, s21, v32
	v_mul_f32_e32 v30, s21, v33
	v_cvt_pk_bf16_f32 v29, v29, v30
	v_lshl_add_u64 v[30:31], v[34:35], 0, v[138:139]
	v_mul_f32_e32 v18, s21, v18
	v_mul_f32_e32 v19, s21, v19
	global_store_dwordx4 v[30:31], v[26:29], off
	v_cvt_pk_bf16_f32 v18, v18, v19
	v_mul_f32_e32 v19, s21, v20
	v_mul_f32_e32 v20, s21, v21
	v_mul_f32_e32 v10, s21, v10
	v_cvt_pk_bf16_f32 v19, v19, v20
	v_mul_f32_e32 v11, s21, v11
	v_cvt_pk_bf16_f32 v20, v10, v11
	v_mul_f32_e32 v10, s21, v12
	v_mul_f32_e32 v11, s21, v13
	v_cvt_pk_bf16_f32 v21, v10, v11
	v_add_u32_e32 v10, s23, v155
	v_ashrrev_i32_e32 v11, 31, v10
	v_lshlrev_b64 v[10:11], 11, v[10:11]
	global_store_dwordx4 v[30:31], v[18:21], off offset:256
	v_mul_f32_e32 v12, s21, v25
	v_mul_f32_e32 v13, s21, v15
	v_lshl_add_u64 v[18:19], s[2:3], 0, v[10:11]
	v_mul_f32_e32 v10, s21, v22
	v_mul_f32_e32 v11, s21, v23
	v_cvt_pk_bf16_f32 v10, v10, v11
	v_mul_f32_e32 v11, s21, v24
	v_cvt_pk_bf16_f32 v11, v11, v12
	v_mul_f32_e32 v12, s21, v14
	v_cvt_pk_bf16_f32 v12, v12, v13
	v_mul_f32_e32 v13, s21, v16
	v_mul_f32_e32 v14, s21, v17
	v_cvt_pk_bf16_f32 v13, v13, v14
	v_lshl_add_u64 v[14:15], v[18:19], 0, v[138:139]
	v_mul_f32_e32 v6, s21, v6
	v_mul_f32_e32 v7, s21, v7
	global_store_dwordx4 v[14:15], v[10:13], off
	v_cvt_pk_bf16_f32 v6, v6, v7
	v_mul_f32_e32 v7, s21, v8
	v_mul_f32_e32 v8, s21, v9
	v_mul_f32_e32 v2, s21, v2
	v_mul_f32_e32 v3, s21, v3
	s_andn2_b64 vcc, exec, s[4:5]
	s_mov_b64 s[2:3], -1
	v_cvt_pk_bf16_f32 v7, v7, v8
	v_cvt_pk_bf16_f32 v8, v2, v3
	v_mul_f32_e32 v2, s21, v4
	v_mul_f32_e32 v3, s21, v5
	v_cvt_pk_bf16_f32 v9, v2, v3
	global_store_dwordx4 v[14:15], v[6:9], off offset:256
	s_cbranch_vccnz .LBB0_172
	s_andn2_b64 vcc, exec, s[8:9]
	s_cbranch_vccnz .LBB0_171
	s_barrier
	s_branch .LBB0_171
; __device__ __forceinline__ unsigned cvt_pk_bf16(float lo, float hi) { unsigned r; asm volatile("v_cvt_pk_bf16_f32 %0, %1, %2" : "=v"(r) : "v"(lo), "v"(hi)); return r; }
;     __device__ __forceinline__ void operator()(const pg8::f32x4 (&acc_)[2][2][4][2], const pg8::Unit& u, int, int wr, int wc, int fr, int fq) const {
;     ...
; #pragma unroll
;         for (int ai = 0; ai < 2; ++ai)
; #pragma unroll
;             for (int m = 0; m < 4; ++m) {
;                 const int grow = u.pm * 256 + ai * 128 + wr * 64 + m * 16 + fr;
; #pragma unroll
;                 for (int bj = 0; bj < 2; ++bj) {
;                     const int cc = cc0 + bj * 128;
;                     const pg8::f32x4 v0 = acc[ai][bj][m][0], v1 = acc[ai][bj][m][1];
;                     u32x4 w; w.x = pg8::cvt_pk_bf16(v0[0] * sc, v0[1] * sc); w.y = pg8::cvt_pk_bf16(v0[2] * sc, v0[3] * sc); w.z = pg8::cvt_pk_bf16(v1[0] * sc, v1[1] * sc); w.w = pg8::cvt_pk_bf16(v1[2] * sc, v1[3] * sc);
;                     *(u32x4*)(bbuf + (size_t)grow * D + cc) = w;
.Lepi1_l0:
	s_lshl_b32 s23, s51, 8
	s_and_b32 s23, s23, 0x300
	v_or_b32_e32 v138, s23, v156
	s_lshl_b32 s23, s28, 8
	v_add_u32_e32 v160, s23, v1
	v_ashrrev_i32_e32 v161, 31, v160
	v_lshlrev_b64 v[160:161], 11, v[160:161]
	v_cvt_pk_bf16_f32 v126, v126, v127
	v_lshl_add_u64 v[160:161], s[2:3], 0, v[160:161]
	v_cvt_pk_bf16_f32 v127, v128, v129
	v_cvt_pk_bf16_f32 v128, v122, v123
	v_lshlrev_b32_e32 v138, 1, v138
	v_cvt_pk_bf16_f32 v129, v124, v125
	v_lshl_add_u64 v[122:123], v[160:161], 0, v[138:139]
	global_store_dwordx4 v[122:123], v[126:129], off
	s_nop 1
	v_cvt_pk_bf16_f32 v114, v114, v115
	v_cvt_pk_bf16_f32 v115, v116, v117
	v_cvt_pk_bf16_f32 v116, v106, v107
	v_cvt_pk_bf16_f32 v117, v108, v109
	v_add_u32_e32 v106, s23, v149
	v_ashrrev_i32_e32 v107, 31, v106
	v_lshlrev_b64 v[106:107], 11, v[106:107]
	global_store_dwordx4 v[122:123], v[114:117], off offset:256
	s_nop 1
	v_lshl_add_u64 v[114:115], s[2:3], 0, v[106:107]
	v_cvt_pk_bf16_f32 v106, v118, v119
	v_cvt_pk_bf16_f32 v107, v120, v121
	v_cvt_pk_bf16_f32 v108, v110, v111
	v_cvt_pk_bf16_f32 v109, v112, v113
	v_lshl_add_u64 v[110:111], v[114:115], 0, v[138:139]
	global_store_dwordx4 v[110:111], v[106:109], off
	s_nop 1
	v_cvt_pk_bf16_f32 v98, v98, v99
	v_cvt_pk_bf16_f32 v99, v100, v101
	v_cvt_pk_bf16_f32 v100, v90, v91
	v_cvt_pk_bf16_f32 v101, v92, v93
	v_add_u32_e32 v90, s23, v150
	v_ashrrev_i32_e32 v91, 31, v90
	v_lshlrev_b64 v[90:91], 11, v[90:91]
	global_store_dwordx4 v[110:111], v[98:101], off offset:256
	s_nop 1
	v_lshl_add_u64 v[98:99], s[2:3], 0, v[90:91]
	v_cvt_pk_bf16_f32 v90, v102, v103
	v_cvt_pk_bf16_f32 v91, v104, v105
	v_cvt_pk_bf16_f32 v92, v94, v95
	v_cvt_pk_bf16_f32 v93, v96, v97
	v_lshl_add_u64 v[94:95], v[98:99], 0, v[138:139]
	global_store_dwordx4 v[94:95], v[90:93], off
	s_nop 1
	v_cvt_pk_bf16_f32 v82, v82, v83
	v_cvt_pk_bf16_f32 v83, v84, v85
	v_cvt_pk_bf16_f32 v84, v74, v75
	v_cvt_pk_bf16_f32 v85, v76, v77
	v_add_u32_e32 v74, s23, v151
	v_ashrrev_i32_e32 v75, 31, v74
	v_lshlrev_b64 v[74:75], 11, v[74:75]
	global_store_dwordx4 v[94:95], v[82:85], off offset:256
	s_nop 1
	v_lshl_add_u64 v[82:83], s[2:3], 0, v[74:75]
	v_cvt_pk_bf16_f32 v74, v86, v87
	v_cvt_pk_bf16_f32 v75, v88, v89
	v_cvt_pk_bf16_f32 v76, v78, v79
	v_cvt_pk_bf16_f32 v77, v80, v81
	v_lshl_add_u64 v[78:79], v[82:83], 0, v[138:139]
	global_store_dwordx4 v[78:79], v[74:77], off
	s_nop 1
	v_cvt_pk_bf16_f32 v70, v70, v71
	v_cvt_pk_bf16_f32 v71, v72, v73
	v_cvt_pk_bf16_f32 v72, v66, v67
	v_cvt_pk_bf16_f32 v73, v68, v69
	v_add_u32_e32 v66, s23, v152
	v_ashrrev_i32_e32 v67, 31, v66
	global_store_dwordx4 v[78:79], v[70:73], off offset:256
	s_nop 1
	v_lshlrev_b64 v[66:67], 11, v[66:67]
	v_cvt_pk_bf16_f32 v62, v62, v63
	v_lshl_add_u64 v[66:67], s[2:3], 0, v[66:67]
	v_cvt_pk_bf16_f32 v63, v64, v65
	v_cvt_pk_bf16_f32 v64, v58, v59
	v_cvt_pk_bf16_f32 v65, v60, v61
	v_lshl_add_u64 v[58:59], v[66:67], 0, v[138:139]
	global_store_dwordx4 v[58:59], v[62:65], off
	s_nop 1
	v_cvt_pk_bf16_f32 v50, v50, v51
	v_cvt_pk_bf16_f32 v51, v52, v53
	v_cvt_pk_bf16_f32 v52, v42, v43
	v_cvt_pk_bf16_f32 v53, v44, v45
	v_add_u32_e32 v42, s23, v153
	v_ashrrev_i32_e32 v43, 31, v42
	v_lshlrev_b64 v[42:43], 11, v[42:43]
	global_store_dwordx4 v[58:59], v[50:53], off offset:256
	s_nop 1
	v_lshl_add_u64 v[50:51], s[2:3], 0, v[42:43]
	v_cvt_pk_bf16_f32 v42, v54, v55
	v_cvt_pk_bf16_f32 v43, v56, v57
	v_cvt_pk_bf16_f32 v44, v46, v47
	v_cvt_pk_bf16_f32 v45, v48, v49
	v_lshl_add_u64 v[46:47], v[50:51], 0, v[138:139]
	global_store_dwordx4 v[46:47], v[42:45], off
	s_nop 1
	v_cvt_pk_bf16_f32 v34, v34, v35
	v_cvt_pk_bf16_f32 v35, v36, v37
	v_cvt_pk_bf16_f32 v36, v26, v27
	v_cvt_pk_bf16_f32 v37, v28, v29
	v_add_u32_e32 v26, s23, v154
	v_ashrrev_i32_e32 v27, 31, v26
	v_lshlrev_b64 v[26:27], 11, v[26:27]
	global_store_dwordx4 v[46:47], v[34:37], off offset:256
	s_nop 1
	v_lshl_add_u64 v[34:35], s[2:3], 0, v[26:27]
	v_cvt_pk_bf16_f32 v26, v38, v39
	v_cvt_pk_bf16_f32 v27, v40, v41
	v_cvt_pk_bf16_f32 v28, v30, v31
	v_cvt_pk_bf16_f32 v29, v32, v33
	v_lshl_add_u64 v[30:31], v[34:35], 0, v[138:139]
	global_store_dwordx4 v[30:31], v[26:29], off
	s_nop 1
	v_cvt_pk_bf16_f32 v18, v18, v19
	v_cvt_pk_bf16_f32 v19, v20, v21
	v_cvt_pk_bf16_f32 v20, v10, v11
	v_cvt_pk_bf16_f32 v21, v12, v13
	v_add_u32_e32 v10, s23, v155
	v_ashrrev_i32_e32 v11, 31, v10
	v_lshlrev_b64 v[10:11], 11, v[10:11]
	global_store_dwordx4 v[30:31], v[18:21], off offset:256
	s_nop 1
	v_lshl_add_u64 v[18:19], s[2:3], 0, v[10:11]
	v_cvt_pk_bf16_f32 v10, v22, v23
	v_cvt_pk_bf16_f32 v11, v24, v25
	v_cvt_pk_bf16_f32 v12, v14, v15
	v_cvt_pk_bf16_f32 v13, v16, v17
	v_lshl_add_u64 v[14:15], v[18:19], 0, v[138:139]
	global_store_dwordx4 v[14:15], v[10:13], off
	s_nop 1
	v_cvt_pk_bf16_f32 v6, v6, v7
	s_andn2_b64 vcc, exec, s[4:5]
	s_mov_b64 s[2:3], -1
	v_cvt_pk_bf16_f32 v7, v8, v9
	v_cvt_pk_bf16_f32 v8, v2, v3
	v_cvt_pk_bf16_f32 v9, v4, v5
	global_store_dwordx4 v[14:15], v[6:9], off offset:256
	s_nop 1
	s_cbranch_vccnz .LBB0_172
	s_andn2_b64 vcc, exec, s[8:9]
	s_cbranch_vccnz .LBB0_171
	s_barrier
	s_branch .LBB0_171

; __device__ __forceinline__ unsigned cvt_pk_bf16(float lo, float hi) { unsigned r; asm volatile("v_cvt_pk_bf16_f32 %0, %1, %2" : "=v"(r) : "v"(lo), "v"(hi)); return r; }
;     __device__ __forceinline__ void operator()(const pg8::f32x4 (&acc_)[2][2][4][2], const pg8::Unit& u, int, int wr, int wc, int fr, int fq) const {
;     ...
;         pg8::f32x4 acc[2][2][4][2];
; #pragma unroll
;         for (int ai = 0; ai < 2; ++ai)
; #pragma unroll
;             for (int m = 0; m < 4; ++m) { const float rs = rstd ? rstd[u.pm * 256 + ai * 128 + wr * 64 + m * 16 + fr] : 1.0f;
; #pragma unroll
;                 for (int bj = 0; bj < 2; ++bj)
; #pragma unroll
;                     for (int n = 0; n < 2; ++n) acc[ai][bj][m][n] = acc_[ai][bj][m][n] * rs; }
; #pragma unroll
;         for (int ai = 0; ai < 2; ++ai)
; #pragma unroll
;             for (int m = 0; m < 4; ++m) {
;                 const int grow = u.pm * 256 + ai * 128 + wr * 64 + m * 16 + fr;
; #pragma unroll
;                 for (int bj = 0; bj < 2; ++bj) {
;                     const int cc = cc0 + bj * 128;
;                     const pg8::f32x4 v0 = acc[ai][bj][m][0], v1 = acc[ai][bj][m][1];
;                     u32x4 w; w.x = pg8::cvt_pk_bf16(v0[0] * sc, v0[1] * sc); w.y = pg8::cvt_pk_bf16(v0[2] * sc, v0[3] * sc); w.z = pg8::cvt_pk_bf16(v1[0] * sc, v1[1] * sc); w.w = pg8::cvt_pk_bf16(v1[2] * sc, v1[3] * sc);
;                     *(u32x4*)(bbuf + (size_t)grow * D + cc) = w;
.Lrs_join_l1:
	s_cmp_eq_u32 s23, 1.0
	s_cbranch_scc1 .Lepi1_l1
	s_lshl_b32 s30, s53, 8
	s_and_b32 s30, s30, 0x300
	v_or_b32_e32 v177, s30, v160
	s_andn2_b64 vcc, exec, s[4:5]
	v_pk_mul_f32 v[126:127], v[126:127], v[138:139] op_sel_hi:[1,0]
	v_pk_mul_f32 v[128:129], v[128:129], v[138:139] op_sel_hi:[1,0]
	v_pk_mul_f32 v[120:121], v[120:121], v[166:167] op_sel_hi:[1,0]
	v_pk_mul_f32 v[118:119], v[118:119], v[166:167] op_sel_hi:[1,0]
	v_pk_mul_f32 v[116:117], v[116:117], v[166:167] op_sel_hi:[1,0]
	v_pk_mul_f32 v[114:115], v[114:115], v[166:167] op_sel_hi:[1,0]
	v_pk_mul_f32 v[92:93], v[92:93], v[166:167] op_sel_hi:[1,0]
	v_pk_mul_f32 v[90:91], v[90:91], v[166:167] op_sel_hi:[1,0]
	v_pk_mul_f32 v[84:85], v[84:85], v[166:167] op_sel_hi:[1,0]
	v_pk_mul_f32 v[82:83], v[82:83], v[166:167] op_sel_hi:[1,0]
	v_pk_mul_f32 v[180:181], v[28:29], v[174:175] op_sel_hi:[1,0]
	v_pk_mul_f32 v[166:167], v[44:45], v[172:173] op_sel_hi:[1,0]
	v_pk_mul_f32 v[28:29], v[14:15], v[176:177] op_sel_hi:[1,0]
	v_pk_mul_f32 v[44:45], v[24:25], v[174:175] op_sel_hi:[1,0]
	v_pk_mul_f32 v[24:25], v[16:17], v[176:177] op_sel_hi:[1,0]
	v_pk_mul_f32 v[122:123], v[122:123], v[138:139] op_sel_hi:[1,0]
	v_pk_mul_f32 v[14:15], v[18:19], v[178:179] op_sel_hi:[1,0]
	v_lshlrev_b64 v[18:19], 11, v[164:165]
	v_pk_mul_f32 v[16:17], v[30:31], v[178:179] op_sel_hi:[1,0]
	v_lshl_add_u64 v[30:31], s[2:3], 0, v[18:19]
	v_mul_f32_e32 v18, s23, v126
	v_mul_f32_e32 v19, s23, v127
	v_pk_mul_f32 v[182:183], v[26:27], v[174:175] op_sel_hi:[1,0]
	v_pk_mul_f32 v[26:27], v[10:11], v[176:177] op_sel_hi:[1,0]
	v_pk_mul_f32 v[10:11], v[20:21], v[178:179] op_sel_hi:[1,0]
	v_cvt_pk_bf16_f32 v18, v18, v19
	v_mul_f32_e32 v19, s23, v128
	v_mul_f32_e32 v20, s23, v129
	v_pk_mul_f32 v[124:125], v[124:125], v[138:139] op_sel_hi:[1,0]
	v_pk_mul_f32 v[108:109], v[108:109], v[138:139] op_sel_hi:[1,0]
	v_pk_mul_f32 v[106:107], v[106:107], v[138:139] op_sel_hi:[1,0]
	v_pk_mul_f32 v[100:101], v[100:101], v[138:139] op_sel_hi:[1,0]
	v_pk_mul_f32 v[98:99], v[98:99], v[138:139] op_sel_hi:[1,0]
	v_cvt_pk_bf16_f32 v19, v19, v20
	v_mul_f32_e32 v20, s23, v122
	v_mul_f32_e32 v21, s23, v123
	v_lshlrev_b32_e32 v138, 1, v177
	v_cvt_pk_bf16_f32 v20, v20, v21
	v_mul_f32_e32 v21, s23, v124
	v_lshl_add_u64 v[30:31], v[30:31], 0, v[138:139]
	v_pk_mul_f32 v[56:57], v[56:57], v[174:175] op_sel_hi:[1,0]
	v_pk_mul_f32 v[54:55], v[54:55], v[174:175] op_sel_hi:[1,0]
	v_pk_mul_f32 v[52:53], v[52:53], v[174:175] op_sel_hi:[1,0]
	v_pk_mul_f32 v[50:51], v[50:51], v[174:175] op_sel_hi:[1,0]
	v_pk_mul_f32 v[174:175], v[22:23], v[174:175] op_sel_hi:[1,0]
	v_pk_mul_f32 v[22:23], v[12:13], v[176:177] op_sel_hi:[1,0]
	v_pk_mul_f32 v[12:13], v[32:33], v[178:179] op_sel_hi:[1,0]
	v_mul_f32_e32 v32, s23, v125
	v_cvt_pk_bf16_f32 v21, v21, v32
	global_store_dwordx4 v[30:31], v[18:21], off
	v_mul_f32_e32 v32, s23, v101
	v_pk_mul_f32 v[110:111], v[110:111], v[168:169] op_sel_hi:[1,0]
	v_mul_f32_e32 v18, s23, v106
	v_mul_f32_e32 v19, s23, v107
	v_cvt_pk_bf16_f32 v18, v18, v19
	v_mul_f32_e32 v19, s23, v108
	v_mul_f32_e32 v20, s23, v109
	v_cvt_pk_bf16_f32 v19, v19, v20
	v_mul_f32_e32 v20, s23, v98
	v_mul_f32_e32 v21, s23, v99
	v_cvt_pk_bf16_f32 v20, v20, v21
	v_mul_f32_e32 v21, s23, v100
	v_cvt_pk_bf16_f32 v21, v21, v32
	global_store_dwordx4 v[30:31], v[18:21], off offset:256
	v_mul_f32_e32 v32, s23, v117
	v_pk_mul_f32 v[112:113], v[112:113], v[168:169] op_sel_hi:[1,0]
	v_add_u32_e32 v18, s25, v157
	v_ashrrev_i32_e32 v19, 31, v18
	v_lshlrev_b64 v[18:19], 11, v[18:19]
	v_lshl_add_u64 v[30:31], s[2:3], 0, v[18:19]
	v_mul_f32_e32 v18, s23, v118
	v_mul_f32_e32 v19, s23, v119
	v_cvt_pk_bf16_f32 v18, v18, v19
	v_mul_f32_e32 v19, s23, v120
	v_mul_f32_e32 v20, s23, v121
	v_cvt_pk_bf16_f32 v19, v19, v20
	v_mul_f32_e32 v20, s23, v114
	v_mul_f32_e32 v21, s23, v115
	v_cvt_pk_bf16_f32 v20, v20, v21
	v_mul_f32_e32 v21, s23, v116
	v_lshl_add_u64 v[30:31], v[30:31], 0, v[138:139]
	v_cvt_pk_bf16_f32 v21, v21, v32
	global_store_dwordx4 v[30:31], v[18:21], off
	v_mul_f32_e32 v32, s23, v85
	v_pk_mul_f32 v[102:103], v[102:103], v[168:169] op_sel_hi:[1,0]
	v_mul_f32_e32 v18, s23, v90
	v_mul_f32_e32 v19, s23, v91
	v_cvt_pk_bf16_f32 v18, v18, v19
	v_mul_f32_e32 v19, s23, v92
	v_mul_f32_e32 v20, s23, v93
	v_cvt_pk_bf16_f32 v19, v19, v20
	v_mul_f32_e32 v20, s23, v82
	v_mul_f32_e32 v21, s23, v83
	v_cvt_pk_bf16_f32 v20, v20, v21
	v_mul_f32_e32 v21, s23, v84
	v_cvt_pk_bf16_f32 v21, v21, v32
	global_store_dwordx4 v[30:31], v[18:21], off offset:256
	v_pk_mul_f32 v[104:105], v[104:105], v[168:169] op_sel_hi:[1,0]
	v_pk_mul_f32 v[78:79], v[78:79], v[168:169] op_sel_hi:[1,0]
	v_add_u32_e32 v18, s25, v158
	v_ashrrev_i32_e32 v19, 31, v18
	v_lshlrev_b64 v[18:19], 11, v[18:19]
	v_lshl_add_u64 v[30:31], s[2:3], 0, v[18:19]
	v_mul_f32_e32 v18, s23, v110
	v_mul_f32_e32 v19, s23, v111
	v_cvt_pk_bf16_f32 v18, v18, v19
	v_mul_f32_e32 v19, s23, v112
	v_mul_f32_e32 v20, s23, v113
	v_cvt_pk_bf16_f32 v19, v19, v20
	v_mul_f32_e32 v20, s23, v102
	v_mul_f32_e32 v21, s23, v103
	v_cvt_pk_bf16_f32 v20, v20, v21
	v_mul_f32_e32 v21, s23, v104
	v_lshl_add_u64 v[30:31], v[30:31], 0, v[138:139]
	v_pk_mul_f32 v[80:81], v[80:81], v[168:169] op_sel_hi:[1,0]
	v_mul_f32_e32 v32, s23, v105
	v_cvt_pk_bf16_f32 v21, v21, v32
	global_store_dwordx4 v[30:31], v[18:21], off
	v_pk_mul_f32 v[74:75], v[74:75], v[168:169] op_sel_hi:[1,0]
	v_pk_mul_f32 v[76:77], v[76:77], v[168:169] op_sel_hi:[1,0]
	v_mul_f32_e32 v18, s23, v78
	v_mul_f32_e32 v19, s23, v79
	v_cvt_pk_bf16_f32 v18, v18, v19
	v_mul_f32_e32 v19, s23, v80
	v_mul_f32_e32 v20, s23, v81
	v_cvt_pk_bf16_f32 v19, v19, v20
	v_mul_f32_e32 v20, s23, v74
	v_mul_f32_e32 v21, s23, v75
; __device__ __forceinline__ unsigned cvt_pk_bf16(float lo, float hi) { unsigned r; asm volatile("v_cvt_pk_bf16_f32 %0, %1, %2" : "=v"(r) : "v"(lo), "v"(hi)); return r; }
;     __device__ __forceinline__ void operator()(const pg8::f32x4 (&acc_)[2][2][4][2], const pg8::Unit& u, int, int wr, int wc, int fr, int fq) const {
;     ...
; #pragma unroll
;         for (int ai = 0; ai < 2; ++ai)
; #pragma unroll
;             for (int m = 0; m < 4; ++m) {
;                 const int grow = u.pm * 256 + ai * 128 + wr * 64 + m * 16 + fr;
; #pragma unroll
;                 for (int bj = 0; bj < 2; ++bj) {
;                     const int cc = cc0 + bj * 128;
;                     const pg8::f32x4 v0 = acc[ai][bj][m][0], v1 = acc[ai][bj][m][1];
;                     u32x4 w; w.x = pg8::cvt_pk_bf16(v0[0] * sc, v0[1] * sc); w.y = pg8::cvt_pk_bf16(v0[2] * sc, v0[3] * sc); w.z = pg8::cvt_pk_bf16(v1[0] * sc, v1[1] * sc); w.w = pg8::cvt_pk_bf16(v1[2] * sc, v1[3] * sc);
;                     *(u32x4*)(bbuf + (size_t)grow * D + cc) = w;
	v_cvt_pk_bf16_f32 v20, v20, v21
	v_mul_f32_e32 v21, s23, v76
	v_mul_f32_e32 v32, s23, v77
	v_cvt_pk_bf16_f32 v21, v21, v32
	global_store_dwordx4 v[30:31], v[18:21], off offset:256
	v_pk_mul_f32 v[94:95], v[94:95], v[170:171] op_sel_hi:[1,0]
	v_pk_mul_f32 v[96:97], v[96:97], v[170:171] op_sel_hi:[1,0]
	v_add_u32_e32 v18, s25, v159
	v_ashrrev_i32_e32 v19, 31, v18
	v_lshlrev_b64 v[18:19], 11, v[18:19]
	v_lshl_add_u64 v[30:31], s[2:3], 0, v[18:19]
	v_mul_f32_e32 v18, s23, v94
	v_mul_f32_e32 v19, s23, v95
	v_pk_mul_f32 v[86:87], v[86:87], v[170:171] op_sel_hi:[1,0]
	v_cvt_pk_bf16_f32 v18, v18, v19
	v_mul_f32_e32 v19, s23, v96
	v_mul_f32_e32 v20, s23, v97
	v_pk_mul_f32 v[88:89], v[88:89], v[170:171] op_sel_hi:[1,0]
	v_cvt_pk_bf16_f32 v19, v19, v20
	v_mul_f32_e32 v20, s23, v86
	v_mul_f32_e32 v21, s23, v87
	v_pk_mul_f32 v[70:71], v[70:71], v[170:171] op_sel_hi:[1,0]
	v_cvt_pk_bf16_f32 v20, v20, v21
	v_mul_f32_e32 v21, s23, v88
	v_lshl_add_u64 v[30:31], v[30:31], 0, v[138:139]
	v_pk_mul_f32 v[72:73], v[72:73], v[170:171] op_sel_hi:[1,0]
	v_mul_f32_e32 v32, s23, v89
	v_cvt_pk_bf16_f32 v21, v21, v32
	global_store_dwordx4 v[30:31], v[18:21], off
	v_pk_mul_f32 v[66:67], v[66:67], v[170:171] op_sel_hi:[1,0]
	v_pk_mul_f32 v[68:69], v[68:69], v[170:171] op_sel_hi:[1,0]
	v_mul_f32_e32 v18, s23, v70
	v_mul_f32_e32 v19, s23, v71
	v_cvt_pk_bf16_f32 v18, v18, v19
	v_mul_f32_e32 v19, s23, v72
	v_mul_f32_e32 v20, s23, v73
	v_cvt_pk_bf16_f32 v19, v19, v20
	v_mul_f32_e32 v20, s23, v66
	v_mul_f32_e32 v21, s23, v67
	v_cvt_pk_bf16_f32 v20, v20, v21
	v_mul_f32_e32 v21, s23, v68
	v_pk_mul_f32 v[62:63], v[62:63], v[172:173] op_sel_hi:[1,0]
	v_mul_f32_e32 v32, s23, v69
	v_cvt_pk_bf16_f32 v21, v21, v32
	global_store_dwordx4 v[30:31], v[18:21], off offset:256
	v_pk_mul_f32 v[64:65], v[64:65], v[172:173] op_sel_hi:[1,0]
	v_pk_mul_f32 v[58:59], v[58:59], v[172:173] op_sel_hi:[1,0]
	v_lshlrev_b64 v[18:19], 11, v[154:155]
	v_lshl_add_u64 v[30:31], s[2:3], 0, v[18:19]
	v_mul_f32_e32 v18, s23, v62
	v_mul_f32_e32 v19, s23, v63
	v_cvt_pk_bf16_f32 v18, v18, v19
	v_mul_f32_e32 v19, s23, v64
	v_mul_f32_e32 v20, s23, v65
	v_pk_mul_f32 v[60:61], v[60:61], v[172:173] op_sel_hi:[1,0]
	v_cvt_pk_bf16_f32 v19, v19, v20
	v_mul_f32_e32 v20, s23, v58
	v_mul_f32_e32 v21, s23, v59
	v_pk_mul_f32 v[168:169], v[42:43], v[172:173] op_sel_hi:[1,0]
	v_cvt_pk_bf16_f32 v20, v20, v21
	v_mul_f32_e32 v21, s23, v60
	v_lshl_add_u64 v[30:31], v[30:31], 0, v[138:139]
	v_mul_f32_e32 v32, s23, v61
	v_cvt_pk_bf16_f32 v21, v21, v32
	global_store_dwordx4 v[30:31], v[18:21], off
	v_pk_mul_f32 v[170:171], v[36:37], v[172:173] op_sel_hi:[1,0]
	v_pk_mul_f32 v[172:173], v[34:35], v[172:173] op_sel_hi:[1,0]
	v_mul_f32_e32 v18, s23, v168
	v_mul_f32_e32 v19, s23, v169
	v_cvt_pk_bf16_f32 v18, v18, v19
	v_mul_f32_e32 v19, s23, v166
	v_mul_f32_e32 v20, s23, v167
	v_cvt_pk_bf16_f32 v19, v19, v20
	v_mul_f32_e32 v20, s23, v172
	v_mul_f32_e32 v21, s23, v173
	v_cvt_pk_bf16_f32 v20, v20, v21
	v_mul_f32_e32 v21, s23, v170
	v_mul_f32_e32 v32, s23, v171
	v_cvt_pk_bf16_f32 v21, v21, v32
	global_store_dwordx4 v[30:31], v[18:21], off offset:256
	v_mul_f32_e32 v32, s23, v53
	v_pk_mul_f32 v[42:43], v[46:47], v[176:177] op_sel_hi:[1,0]
	v_lshlrev_b64 v[18:19], 11, v[152:153]
	v_lshl_add_u64 v[30:31], s[2:3], 0, v[18:19]
	v_mul_f32_e32 v18, s23, v54
	v_mul_f32_e32 v19, s23, v55
	v_cvt_pk_bf16_f32 v18, v18, v19
	v_mul_f32_e32 v19, s23, v56
	v_mul_f32_e32 v20, s23, v57
	v_cvt_pk_bf16_f32 v19, v19, v20
	v_mul_f32_e32 v20, s23, v50
	v_mul_f32_e32 v21, s23, v51
	v_cvt_pk_bf16_f32 v20, v20, v21
	v_mul_f32_e32 v21, s23, v52
	v_lshl_add_u64 v[30:31], v[30:31], 0, v[138:139]
	v_cvt_pk_bf16_f32 v21, v21, v32
	global_store_dwordx4 v[30:31], v[18:21], off
	v_mul_f32_e32 v32, s23, v45
	v_pk_mul_f32 v[36:37], v[48:49], v[176:177] op_sel_hi:[1,0]
	v_mul_f32_e32 v18, s23, v182
	v_mul_f32_e32 v19, s23, v183
	v_cvt_pk_bf16_f32 v18, v18, v19
	v_mul_f32_e32 v19, s23, v180
	v_mul_f32_e32 v20, s23, v181
	v_cvt_pk_bf16_f32 v19, v19, v20
	v_mul_f32_e32 v20, s23, v174
	v_mul_f32_e32 v21, s23, v175
	v_cvt_pk_bf16_f32 v20, v20, v21
	v_mul_f32_e32 v21, s23, v44
	v_cvt_pk_bf16_f32 v21, v21, v32
	global_store_dwordx4 v[30:31], v[18:21], off offset:256
	v_pk_mul_f32 v[38:39], v[38:39], v[176:177] op_sel_hi:[1,0]
	v_pk_mul_f32 v[34:35], v[40:41], v[176:177] op_sel_hi:[1,0]
	v_lshlrev_b64 v[18:19], 11, v[150:151]
	v_lshl_add_u64 v[30:31], s[2:3], 0, v[18:19]
	v_mul_f32_e32 v18, s23, v42
	v_mul_f32_e32 v19, s23, v43
	v_cvt_pk_bf16_f32 v18, v18, v19
	v_mul_f32_e32 v19, s23, v36
	v_mul_f32_e32 v20, s23, v37
	v_cvt_pk_bf16_f32 v19, v19, v20
	v_mul_f32_e32 v20, s23, v38
	v_mul_f32_e32 v21, s23, v39
	v_cvt_pk_bf16_f32 v20, v20, v21
	v_mul_f32_e32 v21, s23, v34
	v_lshl_add_u64 v[30:31], v[30:31], 0, v[138:139]
	v_mul_f32_e32 v32, s23, v35
	v_cvt_pk_bf16_f32 v21, v21, v32
	global_store_dwordx4 v[30:31], v[18:21], off
	v_pk_mul_f32 v[6:7], v[6:7], v[178:179] op_sel_hi:[1,0]
	v_mul_f32_e32 v16, s23, v16
	v_mul_f32_e32 v18, s23, v28
	v_mul_f32_e32 v19, s23, v29
	v_cvt_pk_bf16_f32 v18, v18, v19
	v_mul_f32_e32 v19, s23, v24
	v_mul_f32_e32 v20, s23, v25
	v_cvt_pk_bf16_f32 v19, v19, v20
	v_mul_f32_e32 v20, s23, v26
	v_mul_f32_e32 v21, s23, v27
	v_cvt_pk_bf16_f32 v20, v20, v21
	v_mul_f32_e32 v21, s23, v22
	v_mul_f32_e32 v22, s23, v23
	v_cvt_pk_bf16_f32 v21, v21, v22
	global_store_dwordx4 v[30:31], v[18:21], off offset:256
	v_mul_f32_e32 v17, s23, v17
	v_mul_f32_e32 v12, s23, v12
	v_lshlrev_b64 v[18:19], 11, v[148:149]
	v_lshl_add_u64 v[20:21], s[2:3], 0, v[18:19]
	v_mul_f32_e32 v13, s23, v13
	v_mul_f32_e32 v10, s23, v10
	v_mul_f32_e32 v11, s23, v11
	v_pk_mul_f32 v[8:9], v[8:9], v[178:179] op_sel_hi:[1,0]
	v_pk_mul_f32 v[2:3], v[2:3], v[178:179] op_sel_hi:[1,0]
	v_cvt_pk_bf16_f32 v16, v16, v17
	v_cvt_pk_bf16_f32 v17, v12, v13
	v_mul_f32_e32 v12, s23, v14
	v_mul_f32_e32 v13, s23, v15
	v_cvt_pk_bf16_f32 v18, v12, v13
	v_cvt_pk_bf16_f32 v19, v10, v11
	v_lshl_add_u64 v[10:11], v[20:21], 0, v[138:139]
	v_mul_f32_e32 v6, s23, v6
	v_mul_f32_e32 v7, s23, v7
	v_pk_mul_f32 v[4:5], v[4:5], v[178:179] op_sel_hi:[1,0]
	global_store_dwordx4 v[10:11], v[16:19], off
	v_cvt_pk_bf16_f32 v6, v6, v7
	v_mul_f32_e32 v7, s23, v8
	v_mul_f32_e32 v8, s23, v9
	v_mul_f32_e32 v2, s23, v2
	v_mul_f32_e32 v3, s23, v3
	s_mov_b64 s[2:3], -1
	v_cvt_pk_bf16_f32 v7, v7, v8
	v_cvt_pk_bf16_f32 v8, v2, v3
	v_mul_f32_e32 v2, s23, v4
	v_mul_f32_e32 v3, s23, v5
	v_cvt_pk_bf16_f32 v9, v2, v3
	global_store_dwordx4 v[10:11], v[6:9], off offset:256
	s_cbranch_vccnz .LBB0_833
	s_andn2_b64 vcc, exec, s[8:9]
	s_cbranch_vccnz .LBB0_832
	s_barrier
	s_branch .LBB0_832
; __device__ __forceinline__ unsigned cvt_pk_bf16(float lo, float hi) { unsigned r; asm volatile("v_cvt_pk_bf16_f32 %0, %1, %2" : "=v"(r) : "v"(lo), "v"(hi)); return r; }
;     __device__ __forceinline__ void operator()(const pg8::f32x4 (&acc_)[2][2][4][2], const pg8::Unit& u, int, int wr, int wc, int fr, int fq) const {
;     ...
;         pg8::f32x4 acc[2][2][4][2];
; #pragma unroll
;         for (int ai = 0; ai < 2; ++ai)
; #pragma unroll
;             for (int m = 0; m < 4; ++m) { const float rs = rstd ? rstd[u.pm * 256 + ai * 128 + wr * 64 + m * 16 + fr] : 1.0f;
; #pragma unroll
;                 for (int bj = 0; bj < 2; ++bj)
; #pragma unroll
;                     for (int n = 0; n < 2; ++n) acc[ai][bj][m][n] = acc_[ai][bj][m][n] * rs; }
; #pragma unroll
;         for (int ai = 0; ai < 2; ++ai)
; #pragma unroll
;             for (int m = 0; m < 4; ++m) {
;                 const int grow = u.pm * 256 + ai * 128 + wr * 64 + m * 16 + fr;
; #pragma unroll
;                 for (int bj = 0; bj < 2; ++bj) {
;                     const int cc = cc0 + bj * 128;
;                     const pg8::f32x4 v0 = acc[ai][bj][m][0], v1 = acc[ai][bj][m][1];
;                     u32x4 w; w.x = pg8::cvt_pk_bf16(v0[0] * sc, v0[1] * sc); w.y = pg8::cvt_pk_bf16(v0[2] * sc, v0[3] * sc); w.z = pg8::cvt_pk_bf16(v1[0] * sc, v1[1] * sc); w.w = pg8::cvt_pk_bf16(v1[2] * sc, v1[3] * sc);
;                     *(u32x4*)(bbuf + (size_t)grow * D + cc) = w;
.Lepi1_l1:
	s_lshl_b32 s30, s53, 8
	s_and_b32 s30, s30, 0x300
	v_or_b32_e32 v177, s30, v160
	s_andn2_b64 vcc, exec, s[4:5]
	v_pk_mul_f32 v[126:127], v[126:127], v[138:139] op_sel_hi:[1,0]
	v_pk_mul_f32 v[128:129], v[128:129], v[138:139] op_sel_hi:[1,0]
	v_pk_mul_f32 v[120:121], v[120:121], v[166:167] op_sel_hi:[1,0]
	v_pk_mul_f32 v[118:119], v[118:119], v[166:167] op_sel_hi:[1,0]
	v_pk_mul_f32 v[116:117], v[116:117], v[166:167] op_sel_hi:[1,0]
	v_pk_mul_f32 v[114:115], v[114:115], v[166:167] op_sel_hi:[1,0]
	v_pk_mul_f32 v[92:93], v[92:93], v[166:167] op_sel_hi:[1,0]
	v_pk_mul_f32 v[90:91], v[90:91], v[166:167] op_sel_hi:[1,0]
	v_pk_mul_f32 v[84:85], v[84:85], v[166:167] op_sel_hi:[1,0]
	v_pk_mul_f32 v[82:83], v[82:83], v[166:167] op_sel_hi:[1,0]
	v_pk_mul_f32 v[180:181], v[28:29], v[174:175] op_sel_hi:[1,0]
	v_pk_mul_f32 v[166:167], v[44:45], v[172:173] op_sel_hi:[1,0]
	v_pk_mul_f32 v[28:29], v[14:15], v[176:177] op_sel_hi:[1,0]
	v_pk_mul_f32 v[44:45], v[24:25], v[174:175] op_sel_hi:[1,0]
	v_pk_mul_f32 v[24:25], v[16:17], v[176:177] op_sel_hi:[1,0]
	v_pk_mul_f32 v[122:123], v[122:123], v[138:139] op_sel_hi:[1,0]
	v_pk_mul_f32 v[14:15], v[18:19], v[178:179] op_sel_hi:[1,0]
	v_lshlrev_b64 v[18:19], 11, v[164:165]
	v_pk_mul_f32 v[16:17], v[30:31], v[178:179] op_sel_hi:[1,0]
	v_lshl_add_u64 v[30:31], s[2:3], 0, v[18:19]
	v_pk_mul_f32 v[182:183], v[26:27], v[174:175] op_sel_hi:[1,0]
	v_pk_mul_f32 v[26:27], v[10:11], v[176:177] op_sel_hi:[1,0]
	v_pk_mul_f32 v[10:11], v[20:21], v[178:179] op_sel_hi:[1,0]
	v_cvt_pk_bf16_f32 v18, v126, v127
	v_pk_mul_f32 v[124:125], v[124:125], v[138:139] op_sel_hi:[1,0]
	v_pk_mul_f32 v[108:109], v[108:109], v[138:139] op_sel_hi:[1,0]
	v_pk_mul_f32 v[106:107], v[106:107], v[138:139] op_sel_hi:[1,0]
	v_pk_mul_f32 v[100:101], v[100:101], v[138:139] op_sel_hi:[1,0]
	v_pk_mul_f32 v[98:99], v[98:99], v[138:139] op_sel_hi:[1,0]
	v_cvt_pk_bf16_f32 v19, v128, v129
	v_lshlrev_b32_e32 v138, 1, v177
	v_cvt_pk_bf16_f32 v20, v122, v123
	v_lshl_add_u64 v[30:31], v[30:31], 0, v[138:139]
	v_pk_mul_f32 v[56:57], v[56:57], v[174:175] op_sel_hi:[1,0]
	v_pk_mul_f32 v[54:55], v[54:55], v[174:175] op_sel_hi:[1,0]
	v_pk_mul_f32 v[52:53], v[52:53], v[174:175] op_sel_hi:[1,0]
	v_pk_mul_f32 v[50:51], v[50:51], v[174:175] op_sel_hi:[1,0]
	v_pk_mul_f32 v[174:175], v[22:23], v[174:175] op_sel_hi:[1,0]
	v_pk_mul_f32 v[22:23], v[12:13], v[176:177] op_sel_hi:[1,0]
	v_pk_mul_f32 v[12:13], v[32:33], v[178:179] op_sel_hi:[1,0]
	v_cvt_pk_bf16_f32 v21, v124, v125
	global_store_dwordx4 v[30:31], v[18:21], off
	s_nop 1
	v_pk_mul_f32 v[110:111], v[110:111], v[168:169] op_sel_hi:[1,0]
	v_cvt_pk_bf16_f32 v18, v106, v107
	v_cvt_pk_bf16_f32 v19, v108, v109
	v_cvt_pk_bf16_f32 v20, v98, v99
	v_cvt_pk_bf16_f32 v21, v100, v101
	global_store_dwordx4 v[30:31], v[18:21], off offset:256
	s_nop 1
	v_pk_mul_f32 v[112:113], v[112:113], v[168:169] op_sel_hi:[1,0]
	v_add_u32_e32 v18, s25, v157
	v_ashrrev_i32_e32 v19, 31, v18
	v_lshlrev_b64 v[18:19], 11, v[18:19]
	v_lshl_add_u64 v[30:31], s[2:3], 0, v[18:19]
	v_cvt_pk_bf16_f32 v18, v118, v119
	v_cvt_pk_bf16_f32 v19, v120, v121
	v_cvt_pk_bf16_f32 v20, v114, v115
	v_lshl_add_u64 v[30:31], v[30:31], 0, v[138:139]
	v_cvt_pk_bf16_f32 v21, v116, v117
	global_store_dwordx4 v[30:31], v[18:21], off
	s_nop 1
	v_pk_mul_f32 v[102:103], v[102:103], v[168:169] op_sel_hi:[1,0]
	v_cvt_pk_bf16_f32 v18, v90, v91
	v_cvt_pk_bf16_f32 v19, v92, v93
	v_cvt_pk_bf16_f32 v20, v82, v83
	v_cvt_pk_bf16_f32 v21, v84, v85
	global_store_dwordx4 v[30:31], v[18:21], off offset:256
	s_nop 1
	v_pk_mul_f32 v[104:105], v[104:105], v[168:169] op_sel_hi:[1,0]
	v_pk_mul_f32 v[78:79], v[78:79], v[168:169] op_sel_hi:[1,0]
	v_add_u32_e32 v18, s25, v158
	v_ashrrev_i32_e32 v19, 31, v18
	v_lshlrev_b64 v[18:19], 11, v[18:19]
	v_lshl_add_u64 v[30:31], s[2:3], 0, v[18:19]
	v_cvt_pk_bf16_f32 v18, v110, v111
	v_cvt_pk_bf16_f32 v19, v112, v113
	v_cvt_pk_bf16_f32 v20, v102, v103
	v_lshl_add_u64 v[30:31], v[30:31], 0, v[138:139]
	v_pk_mul_f32 v[80:81], v[80:81], v[168:169] op_sel_hi:[1,0]
	v_cvt_pk_bf16_f32 v21, v104, v105
	global_store_dwordx4 v[30:31], v[18:21], off
	s_nop 1
	v_pk_mul_f32 v[74:75], v[74:75], v[168:169] op_sel_hi:[1,0]
	v_pk_mul_f32 v[76:77], v[76:77], v[168:169] op_sel_hi:[1,0]
	v_cvt_pk_bf16_f32 v18, v78, v79
	v_cvt_pk_bf16_f32 v19, v80, v81
; __device__ __forceinline__ unsigned cvt_pk_bf16(float lo, float hi) { unsigned r; asm volatile("v_cvt_pk_bf16_f32 %0, %1, %2" : "=v"(r) : "v"(lo), "v"(hi)); return r; }
;     __device__ __forceinline__ void operator()(const pg8::f32x4 (&acc_)[2][2][4][2], const pg8::Unit& u, int, int wr, int wc, int fr, int fq) const {
;     ...
; #pragma unroll
;         for (int ai = 0; ai < 2; ++ai)
; #pragma unroll
;             for (int m = 0; m < 4; ++m) {
;                 const int grow = u.pm * 256 + ai * 128 + wr * 64 + m * 16 + fr;
; #pragma unroll
;                 for (int bj = 0; bj < 2; ++bj) {
;                     const int cc = cc0 + bj * 128;
;                     const pg8::f32x4 v0 = acc[ai][bj][m][0], v1 = acc[ai][bj][m][1];
;                     u32x4 w; w.x = pg8::cvt_pk_bf16(v0[0] * sc, v0[1] * sc); w.y = pg8::cvt_pk_bf16(v0[2] * sc, v0[3] * sc); w.z = pg8::cvt_pk_bf16(v1[0] * sc, v1[1] * sc); w.w = pg8::cvt_pk_bf16(v1[2] * sc, v1[3] * sc);
;                     *(u32x4*)(bbuf + (size_t)grow * D + cc) = w;
	v_cvt_pk_bf16_f32 v20, v74, v75
	v_cvt_pk_bf16_f32 v21, v76, v77
	global_store_dwordx4 v[30:31], v[18:21], off offset:256
	s_nop 1
	v_pk_mul_f32 v[94:95], v[94:95], v[170:171] op_sel_hi:[1,0]
	v_pk_mul_f32 v[96:97], v[96:97], v[170:171] op_sel_hi:[1,0]
	v_add_u32_e32 v18, s25, v159
	v_ashrrev_i32_e32 v19, 31, v18
	v_lshlrev_b64 v[18:19], 11, v[18:19]
	v_lshl_add_u64 v[30:31], s[2:3], 0, v[18:19]
	v_pk_mul_f32 v[86:87], v[86:87], v[170:171] op_sel_hi:[1,0]
	v_cvt_pk_bf16_f32 v18, v94, v95
	v_pk_mul_f32 v[88:89], v[88:89], v[170:171] op_sel_hi:[1,0]
	v_cvt_pk_bf16_f32 v19, v96, v97
	v_pk_mul_f32 v[70:71], v[70:71], v[170:171] op_sel_hi:[1,0]
	v_cvt_pk_bf16_f32 v20, v86, v87
	v_lshl_add_u64 v[30:31], v[30:31], 0, v[138:139]
	v_pk_mul_f32 v[72:73], v[72:73], v[170:171] op_sel_hi:[1,0]
	v_cvt_pk_bf16_f32 v21, v88, v89
	global_store_dwordx4 v[30:31], v[18:21], off
	s_nop 1
	v_pk_mul_f32 v[66:67], v[66:67], v[170:171] op_sel_hi:[1,0]
	v_pk_mul_f32 v[68:69], v[68:69], v[170:171] op_sel_hi:[1,0]
	v_cvt_pk_bf16_f32 v18, v70, v71
	v_cvt_pk_bf16_f32 v19, v72, v73
	v_cvt_pk_bf16_f32 v20, v66, v67
	v_pk_mul_f32 v[62:63], v[62:63], v[172:173] op_sel_hi:[1,0]
	v_cvt_pk_bf16_f32 v21, v68, v69
	global_store_dwordx4 v[30:31], v[18:21], off offset:256
	s_nop 1
	v_pk_mul_f32 v[64:65], v[64:65], v[172:173] op_sel_hi:[1,0]
	v_pk_mul_f32 v[58:59], v[58:59], v[172:173] op_sel_hi:[1,0]
	v_lshlrev_b64 v[18:19], 11, v[154:155]
	v_lshl_add_u64 v[30:31], s[2:3], 0, v[18:19]
	v_cvt_pk_bf16_f32 v18, v62, v63
	v_pk_mul_f32 v[60:61], v[60:61], v[172:173] op_sel_hi:[1,0]
	v_cvt_pk_bf16_f32 v19, v64, v65
	v_pk_mul_f32 v[168:169], v[42:43], v[172:173] op_sel_hi:[1,0]
	v_cvt_pk_bf16_f32 v20, v58, v59
	v_lshl_add_u64 v[30:31], v[30:31], 0, v[138:139]
	v_cvt_pk_bf16_f32 v21, v60, v61
	global_store_dwordx4 v[30:31], v[18:21], off
	s_nop 1
	v_pk_mul_f32 v[170:171], v[36:37], v[172:173] op_sel_hi:[1,0]
	v_pk_mul_f32 v[172:173], v[34:35], v[172:173] op_sel_hi:[1,0]
	v_cvt_pk_bf16_f32 v18, v168, v169
	v_cvt_pk_bf16_f32 v19, v166, v167
	v_cvt_pk_bf16_f32 v20, v172, v173
	v_cvt_pk_bf16_f32 v21, v170, v171
	global_store_dwordx4 v[30:31], v[18:21], off offset:256
	s_nop 1
	v_pk_mul_f32 v[42:43], v[46:47], v[176:177] op_sel_hi:[1,0]
	v_lshlrev_b64 v[18:19], 11, v[152:153]
	v_lshl_add_u64 v[30:31], s[2:3], 0, v[18:19]
	v_cvt_pk_bf16_f32 v18, v54, v55
	v_cvt_pk_bf16_f32 v19, v56, v57
	v_cvt_pk_bf16_f32 v20, v50, v51
	v_lshl_add_u64 v[30:31], v[30:31], 0, v[138:139]
	v_cvt_pk_bf16_f32 v21, v52, v53
	global_store_dwordx4 v[30:31], v[18:21], off
	s_nop 1
	v_pk_mul_f32 v[36:37], v[48:49], v[176:177] op_sel_hi:[1,0]
	v_cvt_pk_bf16_f32 v18, v182, v183
	v_cvt_pk_bf16_f32 v19, v180, v181
	v_cvt_pk_bf16_f32 v20, v174, v175
	v_cvt_pk_bf16_f32 v21, v44, v45
	global_store_dwordx4 v[30:31], v[18:21], off offset:256
	s_nop 1
	v_pk_mul_f32 v[38:39], v[38:39], v[176:177] op_sel_hi:[1,0]
	v_pk_mul_f32 v[34:35], v[40:41], v[176:177] op_sel_hi:[1,0]
	v_lshlrev_b64 v[18:19], 11, v[150:151]
	v_lshl_add_u64 v[30:31], s[2:3], 0, v[18:19]
	v_cvt_pk_bf16_f32 v18, v42, v43
	v_cvt_pk_bf16_f32 v19, v36, v37
	v_cvt_pk_bf16_f32 v20, v38, v39
	v_lshl_add_u64 v[30:31], v[30:31], 0, v[138:139]
	v_cvt_pk_bf16_f32 v21, v34, v35
	global_store_dwordx4 v[30:31], v[18:21], off
	s_nop 1
	v_pk_mul_f32 v[6:7], v[6:7], v[178:179] op_sel_hi:[1,0]
	v_cvt_pk_bf16_f32 v18, v28, v29
	v_cvt_pk_bf16_f32 v19, v24, v25
	v_cvt_pk_bf16_f32 v20, v26, v27
	v_cvt_pk_bf16_f32 v21, v22, v23
	global_store_dwordx4 v[30:31], v[18:21], off offset:256
	s_nop 1
	v_lshlrev_b64 v[18:19], 11, v[148:149]
	v_lshl_add_u64 v[20:21], s[2:3], 0, v[18:19]
	v_pk_mul_f32 v[8:9], v[8:9], v[178:179] op_sel_hi:[1,0]
	v_pk_mul_f32 v[2:3], v[2:3], v[178:179] op_sel_hi:[1,0]
	v_cvt_pk_bf16_f32 v16, v16, v17
	v_cvt_pk_bf16_f32 v17, v12, v13
	v_cvt_pk_bf16_f32 v18, v14, v15
	v_cvt_pk_bf16_f32 v19, v10, v11
	v_lshl_add_u64 v[10:11], v[20:21], 0, v[138:139]
	v_pk_mul_f32 v[4:5], v[4:5], v[178:179] op_sel_hi:[1,0]
	global_store_dwordx4 v[10:11], v[16:19], off
	s_nop 1
	v_cvt_pk_bf16_f32 v6, v6, v7
	s_mov_b64 s[2:3], -1
	v_cvt_pk_bf16_f32 v7, v8, v9
	v_cvt_pk_bf16_f32 v8, v2, v3
	v_cvt_pk_bf16_f32 v9, v4, v5
	global_store_dwordx4 v[10:11], v[6:9], off offset:256
	s_nop 1
	s_cbranch_vccnz .LBB0_833
	s_andn2_b64 vcc, exec, s[8:9]
	s_cbranch_vccnz .LBB0_832
	s_barrier
	s_branch .LBB0_832
